# attention loop: PV MFMAs of each query sub-tile start as soon as their first packed P fragments exist (spread through the softmax VALU stream)
# speedup vs baseline: 1.0233x; 1.0101x over previous
.Lat_nr1:
	v_sub_f32_e32 v64, v64, v233
	v_sub_f32_e32 v65, v65, v233
	v_sub_f32_e32 v66, v66, v233
	v_sub_f32_e32 v67, v67, v233
	v_exp_f32_e32 v64, v64
	v_sub_f32_e32 v68, v68, v233
	v_exp_f32_e32 v65, v65
	v_sub_f32_e32 v69, v69, v233
	v_exp_f32_e32 v66, v66
	v_sub_f32_e32 v70, v70, v233
	v_exp_f32_e32 v67, v67
	v_add_f32_e32 v202, v202, v64
	v_sub_f32_e32 v71, v71, v233
	v_exp_f32_e32 v68, v68
	v_sub_f32_e32 v72, v72, v233
	v_exp_f32_e32 v69, v69
	v_add_f32_e32 v202, v202, v66
	v_sub_f32_e32 v73, v73, v233
	v_exp_f32_e32 v70, v70
	v_add_f32_e32 v214, v65, v67
	v_cvt_pk_bf16_f32 v64, v64, v65
	v_sub_f32_e32 v74, v74, v233
	v_exp_f32_e32 v71, v71
	v_add_f32_e32 v202, v202, v68
	v_sub_f32_e32 v75, v75, v233
	v_exp_f32_e32 v72, v72
	v_add_f32_e32 v214, v214, v69
	v_cvt_pk_bf16_f32 v65, v66, v67
	v_sub_f32_e32 v76, v76, v233
	v_exp_f32_e32 v73, v73
	v_add_f32_e32 v202, v202, v70
	v_sub_f32_e32 v77, v77, v233
	v_exp_f32_e32 v74, v74
	v_add_f32_e32 v214, v214, v71
	v_cvt_pk_bf16_f32 v66, v68, v69
	v_sub_f32_e32 v78, v78, v233
	v_exp_f32_e32 v75, v75
	v_add_f32_e32 v202, v202, v72
	v_sub_f32_e32 v79, v79, v233
	v_exp_f32_e32 v76, v76
	v_add_f32_e32 v214, v214, v73
	v_cvt_pk_bf16_f32 v67, v70, v71
	v_sub_f32_e32 v80, v80, v233
	v_exp_f32_e32 v77, v77
	v_mfma_f32_32x32x16_bf16 v[16:31], v[236:239], v[64:67], v[16:31]
	v_add_f32_e32 v202, v202, v74
	v_sub_f32_e32 v81, v81, v233
	v_exp_f32_e32 v78, v78
	v_add_f32_e32 v214, v214, v75
	v_cvt_pk_bf16_f32 v68, v72, v73
	v_sub_f32_e32 v82, v82, v233
	v_exp_f32_e32 v79, v79
	v_add_f32_e32 v202, v202, v76
	v_sub_f32_e32 v83, v83, v233
	v_exp_f32_e32 v80, v80
	v_add_f32_e32 v214, v214, v77
	v_cvt_pk_bf16_f32 v69, v74, v75
	v_mfma_f32_32x32x16_bf16 v[0:15], v[240:243], v[64:67], v[0:15]
	v_sub_f32_e32 v84, v84, v233
	v_exp_f32_e32 v81, v81
	v_add_f32_e32 v202, v202, v78
	v_sub_f32_e32 v85, v85, v233
	v_exp_f32_e32 v82, v82
	v_add_f32_e32 v214, v214, v79
	v_cvt_pk_bf16_f32 v70, v76, v77
	v_sub_f32_e32 v86, v86, v233
	v_exp_f32_e32 v83, v83
	v_add_f32_e32 v202, v202, v80
	v_sub_f32_e32 v87, v87, v233
	v_exp_f32_e32 v84, v84
	v_add_f32_e32 v214, v214, v81
	v_cvt_pk_bf16_f32 v71, v78, v79
	v_sub_f32_e32 v88, v88, v233
	v_exp_f32_e32 v85, v85
	v_mfma_f32_32x32x16_bf16 v[16:31], v[244:247], v[68:71], v[16:31]
	v_add_f32_e32 v202, v202, v82
	v_sub_f32_e32 v89, v89, v233
	v_exp_f32_e32 v86, v86
	v_add_f32_e32 v214, v214, v83
	v_cvt_pk_bf16_f32 v72, v80, v81
	v_sub_f32_e32 v90, v90, v233
	v_exp_f32_e32 v87, v87
	v_add_f32_e32 v202, v202, v84
	v_sub_f32_e32 v91, v91, v233
	v_exp_f32_e32 v88, v88
	v_add_f32_e32 v214, v214, v85
	v_cvt_pk_bf16_f32 v73, v82, v83
	v_mfma_f32_32x32x16_bf16 v[0:15], v[248:251], v[68:71], v[0:15]
	v_sub_f32_e32 v92, v92, v233
	v_exp_f32_e32 v89, v89
	v_add_f32_e32 v202, v202, v86
	v_sub_f32_e32 v93, v93, v233
	v_exp_f32_e32 v90, v90
	v_add_f32_e32 v214, v214, v87
	v_cvt_pk_bf16_f32 v74, v84, v85
	v_sub_f32_e32 v94, v94, v233
	v_exp_f32_e32 v91, v91
	v_add_f32_e32 v202, v202, v88
	v_sub_f32_e32 v95, v95, v233
	v_exp_f32_e32 v92, v92
	v_add_f32_e32 v214, v214, v89
	v_cvt_pk_bf16_f32 v75, v86, v87
	v_exp_f32_e32 v93, v93
	v_add_f32_e32 v202, v202, v90
	v_exp_f32_e32 v94, v94
	v_add_f32_e32 v214, v214, v91
	v_cvt_pk_bf16_f32 v76, v88, v89
	v_exp_f32_e32 v95, v95
	v_add_f32_e32 v202, v202, v92
	v_add_f32_e32 v214, v214, v93
	v_cvt_pk_bf16_f32 v77, v90, v91
	v_add_f32_e32 v202, v202, v94
	v_add_f32_e32 v214, v214, v95
	v_cvt_pk_bf16_f32 v78, v92, v93
	v_cvt_pk_bf16_f32 v79, v94, v95
	v_add_f32_e32 v202, v202, v214
	ds_read_b128 v[80:83], v218 offset:13376
	ds_read_b128 v[84:87], v218 offset:17984
	ds_read_b128 v[88:91], v218 offset:13408
	ds_read_b128 v[92:95], v218 offset:18016
	v_sub_f32_e32 v96, v96, v234
	v_sub_f32_e32 v97, v97, v234
	v_sub_f32_e32 v98, v98, v234
	v_sub_f32_e32 v99, v99, v234
	v_exp_f32_e32 v96, v96
	v_sub_f32_e32 v100, v100, v234
	v_exp_f32_e32 v97, v97
	v_sub_f32_e32 v101, v101, v234
	v_exp_f32_e32 v98, v98
	v_sub_f32_e32 v102, v102, v234
	v_exp_f32_e32 v99, v99
	v_add_f32_e32 v203, v203, v96
	v_sub_f32_e32 v103, v103, v234
	v_exp_f32_e32 v100, v100
	v_sub_f32_e32 v104, v104, v234
	v_exp_f32_e32 v101, v101
	v_add_f32_e32 v203, v203, v98
	v_sub_f32_e32 v105, v105, v234
	v_exp_f32_e32 v102, v102
	v_add_f32_e32 v216, v97, v99
	s_waitcnt lgkmcnt(3)
	v_mfma_f32_32x32x16_bf16 v[16:31], v[80:83], v[72:75], v[16:31]
	v_cvt_pk_bf16_f32 v96, v96, v97
	v_sub_f32_e32 v106, v106, v234
	v_exp_f32_e32 v103, v103
	v_add_f32_e32 v203, v203, v100
	v_sub_f32_e32 v107, v107, v234
	v_exp_f32_e32 v104, v104
	v_add_f32_e32 v216, v216, v101
	v_cvt_pk_bf16_f32 v97, v98, v99
	v_sub_f32_e32 v108, v108, v234
	v_exp_f32_e32 v105, v105
	v_add_f32_e32 v203, v203, v102
	v_sub_f32_e32 v109, v109, v234
	s_waitcnt lgkmcnt(2)
	v_mfma_f32_32x32x16_bf16 v[0:15], v[84:87], v[72:75], v[0:15]
	v_exp_f32_e32 v106, v106
	v_add_f32_e32 v216, v216, v103
	v_cvt_pk_bf16_f32 v98, v100, v101
	v_sub_f32_e32 v110, v110, v234
	v_exp_f32_e32 v107, v107
	v_add_f32_e32 v203, v203, v104
	v_sub_f32_e32 v111, v111, v234
	v_exp_f32_e32 v108, v108
	v_add_f32_e32 v216, v216, v105
	v_cvt_pk_bf16_f32 v99, v102, v103
	v_sub_f32_e32 v112, v112, v234
	v_exp_f32_e32 v109, v109
	s_waitcnt lgkmcnt(1)
	v_mfma_f32_32x32x16_bf16 v[16:31], v[88:91], v[76:79], v[16:31]
	v_add_f32_e32 v203, v203, v106
	v_sub_f32_e32 v113, v113, v234
	v_exp_f32_e32 v110, v110
	v_add_f32_e32 v216, v216, v107
	v_cvt_pk_bf16_f32 v100, v104, v105
	v_sub_f32_e32 v114, v114, v234
	v_exp_f32_e32 v111, v111
	v_add_f32_e32 v203, v203, v108
	v_sub_f32_e32 v115, v115, v234
	v_exp_f32_e32 v112, v112
	v_add_f32_e32 v216, v216, v109
	v_cvt_pk_bf16_f32 v101, v106, v107
	s_waitcnt lgkmcnt(0)
	v_mfma_f32_32x32x16_bf16 v[0:15], v[92:95], v[76:79], v[0:15]
	v_sub_f32_e32 v116, v116, v234
	v_exp_f32_e32 v113, v113
	v_add_f32_e32 v203, v203, v110
	v_sub_f32_e32 v117, v117, v234
	v_exp_f32_e32 v114, v114
	v_add_f32_e32 v216, v216, v111
	v_cvt_pk_bf16_f32 v102, v108, v109
	v_sub_f32_e32 v118, v118, v234
	v_exp_f32_e32 v115, v115
	v_add_f32_e32 v203, v203, v112
	v_sub_f32_e32 v119, v119, v234
	v_exp_f32_e32 v116, v116
	v_mfma_f32_32x32x16_bf16 v[48:63], v[236:239], v[96:99], v[48:63]
	v_add_f32_e32 v216, v216, v113
	v_cvt_pk_bf16_f32 v103, v110, v111
	v_sub_f32_e32 v120, v120, v234
	v_exp_f32_e32 v117, v117
	v_add_f32_e32 v203, v203, v114
	v_sub_f32_e32 v121, v121, v234
	v_exp_f32_e32 v118, v118
	v_add_f32_e32 v216, v216, v115
	v_cvt_pk_bf16_f32 v104, v112, v113
	v_sub_f32_e32 v122, v122, v234
	v_exp_f32_e32 v119, v119
	v_add_f32_e32 v203, v203, v116
	v_mfma_f32_32x32x16_bf16 v[32:47], v[240:243], v[96:99], v[32:47]
	v_sub_f32_e32 v123, v123, v234
	v_exp_f32_e32 v120, v120
	v_add_f32_e32 v216, v216, v117
	v_cvt_pk_bf16_f32 v105, v114, v115
	v_sub_f32_e32 v124, v124, v234
	v_exp_f32_e32 v121, v121
	v_add_f32_e32 v203, v203, v118
	v_sub_f32_e32 v125, v125, v234
	v_exp_f32_e32 v122, v122
	v_add_f32_e32 v216, v216, v119
	v_cvt_pk_bf16_f32 v106, v116, v117
	v_sub_f32_e32 v126, v126, v234
	v_mfma_f32_32x32x16_bf16 v[48:63], v[244:247], v[100:103], v[48:63]
	v_exp_f32_e32 v123, v123
	v_add_f32_e32 v203, v203, v120
	v_sub_f32_e32 v127, v127, v234
	v_exp_f32_e32 v124, v124
	v_add_f32_e32 v216, v216, v121
	v_cvt_pk_bf16_f32 v107, v118, v119
	v_exp_f32_e32 v125, v125
	v_add_f32_e32 v203, v203, v122
	v_exp_f32_e32 v126, v126
	v_add_f32_e32 v216, v216, v123
	v_cvt_pk_bf16_f32 v108, v120, v121
	v_exp_f32_e32 v127, v127
	v_mfma_f32_32x32x16_bf16 v[32:47], v[248:251], v[100:103], v[32:47]
	v_add_f32_e32 v203, v203, v124
	v_add_f32_e32 v216, v216, v125
	v_cvt_pk_bf16_f32 v109, v122, v123
	v_add_f32_e32 v203, v203, v126
	v_add_f32_e32 v216, v216, v127
	v_cvt_pk_bf16_f32 v110, v124, v125
	v_cvt_pk_bf16_f32 v111, v126, v127
	v_add_f32_e32 v203, v203, v216
	s_nop 0
	v_mfma_f32_32x32x16_bf16 v[48:63], v[80:83], v[104:107], v[48:63]
	v_mfma_f32_32x32x16_bf16 v[32:47], v[84:87], v[104:107], v[32:47]
	s_cmp_eq_u32 s1, 64
	s_cbranch_scc1 .Lat_nowr
	s_cmp_eq_u32 s4, 1
	s_cselect_b32 s4, 0x5800, 0
	v_add3_u32 v214, s4, v225, v226
	v_add3_u32 v215, s4, v227, v228
	v_add3_u32 v216, s4, v229, v230
	v_add3_u32 v217, s4, v231, v200
	v_add3_u32 v196, s4, v232, v200
	s_waitcnt vmcnt(4)
	ds_write_b128 v214, v[176:179]
	s_waitcnt vmcnt(3)
	ds_write_b128 v215, v[180:183]
	s_waitcnt vmcnt(2)
	ds_write_b128 v216, v[184:187]
	s_waitcnt vmcnt(1)
	ds_write_b128 v217, v[188:191] offset:13312
	s_waitcnt vmcnt(0)
	ds_write_b128 v196, v[192:195] offset:13312
.Lat_nowr:
	v_mfma_f32_32x32x16_bf16 v[48:63], v[88:91], v[108:111], v[48:63]
	v_mfma_f32_32x32x16_bf16 v[32:47], v[92:95], v[108:111], v[32:47]
	s_add_i32 s1, s1, 1
	v_lshl_add_u64 v[204:205], v[204:205], 0, s[76:77]
	v_lshl_add_u64 v[206:207], v[206:207], 0, s[76:77]
	v_lshl_add_u64 v[208:209], v[208:209], 0, s[54:55]
	v_lshl_add_u64 v[210:211], v[210:211], 0, s[54:55]
	v_lshl_add_u64 v[212:213], v[212:213], 0, s[54:55]
	s_cmpk_eq_i32 s1, 0x41
	s_waitcnt lgkmcnt(0)
	s_barrier
	s_cbranch_scc0 .LBB0_346
	s_nop 7
	s_nop 7
	s_branch .LBB0_343
